# slot routine three items in flight + rebalanced schedule (wa/wb/wo in in-proj slots, P0 w_in only)
# speedup vs baseline: 1.0025x; 1.0025x over previous
; __device__ __forceinline__ void tr_item(const float* __restrict__ W, int K, int N, bf16_t* WT, const float* __restrict__ kscale, int rowmode, int item, int lane) {
;     const int nblk = N >> 5, kb = item / nblk, nb = item - kb * nblk;
;     const int c = lane >> 3, q = lane & 7, k0 = kb * 64 + c * 8, n0 = nb * 32 + q * 4;
;     f32x4 v[8];
; #pragma unroll
;     for (int i = 0; i < 8; ++i) v[i] = __builtin_nontemporal_load((const f32x4*)(W + (size_t)(k0 + i) * N + n0));
;     if (kscale) { const f32x4 s0 = *(const f32x4*)(kscale + k0), s1 = *(const f32x4*)(kscale + k0 + 4);
; #pragma unroll
;         for (int i = 0; i < 4; ++i) { v[i] = v[i] * s0[i]; v[4 + i] = v[4 + i] * s1[i]; } }
;     int drow;
;     if (rowmode == 0) drow = n0;
;     else if (rowmode == 3) { const int g = n0 - pg8::C_GA; drow = g < 0 ? n0 : pg8::C_GA + (((g & 2047) >> 7) << 8) + ((g >> 11) << 7) + (g & 127); }
;     else drow = ((n0 >> 7) << 8) + (n0 & 127) + (rowmode == 2 ? 128 : 0);
.Lsl_in_rmd5:
	s_mul_i32 s19, s19, s41
	s_lshl_b32 s20, s17, 7
	s_add_i32 s19, s19, s20
	v_add_u32_e32 v45, s19, v105
	s_add_i32 s4, s4, 512
	s_cmp_ge_u32 s4, s29
	s_cbranch_scc1 .Lsl_in_pair
	s_add_i32 s16, s4, s44
	s_mul_i32 s17, s16, s38
	s_lshr_b32 s17, s17, s39
	s_mul_i32 s19, s17, s40
	s_sub_i32 s18, s16, s19
	s_mul_i32 s19, s17, s37
	s_lshl_b32 s20, s18, 7
	s_add_i32 s19, s19, s20
	v_add_u32_e32 v42, s19, v104
	s_cmp_eq_u32 s43, 0
	s_cbranch_scc1 .Lsl_in_nks7
	s_lshl_b32 s19, s17, 8
	v_add_u32_e32 v43, s19, v110
	global_load_dwordx4 v[144:147], v43, s[26:27]
	global_load_dwordx4 v[148:151], v43, s[26:27] offset:16
.Lsl_in_nks7:
	global_load_dwordx4 v[112:115], v42, s[22:23] nt
	v_add_u32_e32 v42, s36, v42
	global_load_dwordx4 v[116:119], v42, s[22:23] nt
	v_add_u32_e32 v42, s36, v42
	global_load_dwordx4 v[120:123], v42, s[22:23] nt
	v_add_u32_e32 v42, s36, v42
	global_load_dwordx4 v[124:127], v42, s[22:23] nt
	v_add_u32_e32 v42, s36, v42
	global_load_dwordx4 v[128:131], v42, s[22:23] nt
	v_add_u32_e32 v42, s36, v42
	global_load_dwordx4 v[132:135], v42, s[22:23] nt
	v_add_u32_e32 v42, s36, v42
	global_load_dwordx4 v[136:139], v42, s[22:23] nt
	v_add_u32_e32 v42, s36, v42
	global_load_dwordx4 v[140:143], v42, s[22:23] nt
	s_lshl_b32 s19, s18, 5
	s_cmp_eq_u32 s42, 0
	s_cbranch_scc1 .Lsl_in_rmd8
	s_cmp_eq_u32 s42, 3
	s_cbranch_scc1 .Lsl_in_rm39
	s_lshr_b32 s20, s19, 7
	s_lshl_b32 s20, s20, 8
	s_and_b32 s19, s19, 0x7f
	s_add_i32 s19, s19, s20
	s_and_b32 s20, s42, 2
	s_lshl_b32 s20, s20, 6
	s_add_i32 s19, s19, s20
	s_branch .Lsl_in_rmd8

; __device__ __forceinline__ unsigned cvt_pk_bf16(float lo, float hi) { unsigned r; asm volatile("v_cvt_pk_bf16_f32 %0, %1, %2" : "=v"(r) : "v"(lo), "v"(hi)); return r; }
; __device__ __forceinline__ void st16_wt(void* p, u32x4 v) { asm volatile("global_store_dwordx4 %0, %1, off sc1\n\ts_nop 1" :: "v"(p), "v"(v) : "memory"); }
; __device__ __forceinline__ void tr_item(const float* __restrict__ W, int K, int N, bf16_t* WT, const float* __restrict__ kscale, int rowmode, int item, int lane) {
;     ...
;     else drow = ((n0 >> 7) << 8) + (n0 & 127) + (rowmode == 2 ? 128 : 0);
; #pragma unroll
;     for (int e = 0; e < 4; ++e) { u32x4 o; o.x = cvt_pk_bf16(v[0][e], v[1][e]); o.y = cvt_pk_bf16(v[2][e], v[3][e]); o.z = cvt_pk_bf16(v[4][e], v[5][e]); o.w = cvt_pk_bf16(v[6][e], v[7][e]);
;         pg8::st16_wt(WT + (size_t)(drow + e) * K + k0, o); }
.Lsl_in_rmd8:
	s_mul_i32 s19, s19, s41
	s_lshl_b32 s20, s17, 7
	s_add_i32 s19, s19, s20
	v_add_u32_e32 v111, s19, v105
	s_add_i32 s4, s4, 512
	s_cmp_eq_u32 s43, 0
	s_cbranch_scc1 .Lsl_in_w810
	s_waitcnt vmcnt(20)
	s_branch .Lsl_in_wd11
.Lsl_in_w810:
	s_waitcnt vmcnt(16)

; __device__ __forceinline__ unsigned cvt_pk_bf16(float lo, float hi) { unsigned r; asm volatile("v_cvt_pk_bf16_f32 %0, %1, %2" : "=v"(r) : "v"(lo), "v"(hi)); return r; }
; __device__ __forceinline__ void st16_wt(void* p, u32x4 v) { asm volatile("global_store_dwordx4 %0, %1, off sc1\n\ts_nop 1" :: "v"(p), "v"(v) : "memory"); }
; __device__ __forceinline__ void tr_item(const float* __restrict__ W, int K, int N, bf16_t* WT, const float* __restrict__ kscale, int rowmode, int item, int lane) {
;     ...
;     if (kscale) { const f32x4 s0 = *(const f32x4*)(kscale + k0), s1 = *(const f32x4*)(kscale + k0 + 4);
; #pragma unroll
;         for (int i = 0; i < 4; ++i) { v[i] = v[i] * s0[i]; v[4 + i] = v[4 + i] * s1[i]; } }
;     int drow;
;     if (rowmode == 0) drow = n0;
;     else if (rowmode == 3) { const int g = n0 - pg8::C_GA; drow = g < 0 ? n0 : pg8::C_GA + (((g & 2047) >> 7) << 8) + ((g >> 11) << 7) + (g & 127); }
;     else drow = ((n0 >> 7) << 8) + (n0 & 127) + (rowmode == 2 ? 128 : 0);
; #pragma unroll
;     for (int e = 0; e < 4; ++e) { u32x4 o; o.x = cvt_pk_bf16(v[0][e], v[1][e]); o.y = cvt_pk_bf16(v[2][e], v[3][e]); o.z = cvt_pk_bf16(v[4][e], v[5][e]); o.w = cvt_pk_bf16(v[6][e], v[7][e]);
;         pg8::st16_wt(WT + (size_t)(drow + e) * K + k0, o); }
.Lsl_in_nmul12:
	v_cvt_pk_bf16_f32 v86, v2, v6
	v_cvt_pk_bf16_f32 v87, v10, v14
	v_cvt_pk_bf16_f32 v88, v18, v22
	v_cvt_pk_bf16_f32 v89, v26, v30
	v_cvt_pk_bf16_f32 v90, v3, v7
	v_cvt_pk_bf16_f32 v91, v11, v15
	v_cvt_pk_bf16_f32 v92, v19, v23
	v_cvt_pk_bf16_f32 v93, v27, v31
	v_cvt_pk_bf16_f32 v94, v4, v8
	v_cvt_pk_bf16_f32 v95, v12, v16
	v_cvt_pk_bf16_f32 v96, v20, v24
	v_cvt_pk_bf16_f32 v97, v28, v32
	v_cvt_pk_bf16_f32 v98, v5, v9
	v_cvt_pk_bf16_f32 v99, v13, v17
	v_cvt_pk_bf16_f32 v100, v21, v25
	v_cvt_pk_bf16_f32 v101, v29, v33
	global_store_dwordx4 v44, v[86:89], s[24:25] sc1
	v_add_u32_e32 v44, s41, v44
	global_store_dwordx4 v44, v[90:93], s[24:25] sc1
	v_add_u32_e32 v44, s41, v44
	global_store_dwordx4 v44, v[94:97], s[24:25] sc1
	v_add_u32_e32 v44, s41, v44
	global_store_dwordx4 v44, v[98:101], s[24:25] sc1
	s_cmp_eq_u32 s43, 0
	s_cbranch_scc1 .Lsl_in_w813
	s_waitcnt vmcnt(14)
	s_branch .Lsl_in_wd14
.Lsl_in_w813:
	s_waitcnt vmcnt(12)
.Lsl_in_wd14:
	s_cmp_eq_u32 s43, 0
	s_cbranch_scc1 .Lsl_in_nmul15
	v_mul_f32_e32 v46, v46, v78
	v_mul_f32_e32 v47, v47, v78
	v_mul_f32_e32 v48, v48, v78
	v_mul_f32_e32 v49, v49, v78
	v_mul_f32_e32 v50, v50, v79
	v_mul_f32_e32 v51, v51, v79
	v_mul_f32_e32 v52, v52, v79
	v_mul_f32_e32 v53, v53, v79
	v_mul_f32_e32 v54, v54, v80
	v_mul_f32_e32 v55, v55, v80
	v_mul_f32_e32 v56, v56, v80
	v_mul_f32_e32 v57, v57, v80
	v_mul_f32_e32 v58, v58, v81
	v_mul_f32_e32 v59, v59, v81
	v_mul_f32_e32 v60, v60, v81
	v_mul_f32_e32 v61, v61, v81
	v_mul_f32_e32 v62, v62, v82
	v_mul_f32_e32 v63, v63, v82
	v_mul_f32_e32 v64, v64, v82
	v_mul_f32_e32 v65, v65, v82
	v_mul_f32_e32 v66, v66, v83
	v_mul_f32_e32 v67, v67, v83
	v_mul_f32_e32 v68, v68, v83
	v_mul_f32_e32 v69, v69, v83
	v_mul_f32_e32 v70, v70, v84
	v_mul_f32_e32 v71, v71, v84
	v_mul_f32_e32 v72, v72, v84
	v_mul_f32_e32 v73, v73, v84
	v_mul_f32_e32 v74, v74, v85
	v_mul_f32_e32 v75, v75, v85
	v_mul_f32_e32 v76, v76, v85
	v_mul_f32_e32 v77, v77, v85
.Lsl_in_nmul15:
	v_cvt_pk_bf16_f32 v86, v46, v50
	v_cvt_pk_bf16_f32 v87, v54, v58
	v_cvt_pk_bf16_f32 v88, v62, v66
	v_cvt_pk_bf16_f32 v89, v70, v74
	v_cvt_pk_bf16_f32 v90, v47, v51
	v_cvt_pk_bf16_f32 v91, v55, v59
	v_cvt_pk_bf16_f32 v92, v63, v67
	v_cvt_pk_bf16_f32 v93, v71, v75
	v_cvt_pk_bf16_f32 v94, v48, v52
	v_cvt_pk_bf16_f32 v95, v56, v60
	v_cvt_pk_bf16_f32 v96, v64, v68
	v_cvt_pk_bf16_f32 v97, v72, v76
	v_cvt_pk_bf16_f32 v98, v49, v53
	v_cvt_pk_bf16_f32 v99, v57, v61
	v_cvt_pk_bf16_f32 v100, v65, v69
	v_cvt_pk_bf16_f32 v101, v73, v77
	global_store_dwordx4 v45, v[86:89], s[24:25] sc1
	v_add_u32_e32 v45, s41, v45
	global_store_dwordx4 v45, v[90:93], s[24:25] sc1
	v_add_u32_e32 v45, s41, v45
	global_store_dwordx4 v45, v[94:97], s[24:25] sc1
	v_add_u32_e32 v45, s41, v45
	global_store_dwordx4 v45, v[98:101], s[24:25] sc1
	s_waitcnt vmcnt(8)
	s_cmp_eq_u32 s43, 0
	s_cbranch_scc1 .Lsl_in_nmul16
	v_mul_f32_e32 v112, v112, v144
	v_mul_f32_e32 v113, v113, v144
	v_mul_f32_e32 v114, v114, v144
	v_mul_f32_e32 v115, v115, v144
	v_mul_f32_e32 v116, v116, v145
	v_mul_f32_e32 v117, v117, v145
	v_mul_f32_e32 v118, v118, v145
	v_mul_f32_e32 v119, v119, v145
	v_mul_f32_e32 v120, v120, v146
	v_mul_f32_e32 v121, v121, v146
	v_mul_f32_e32 v122, v122, v146
	v_mul_f32_e32 v123, v123, v146
	v_mul_f32_e32 v124, v124, v147
	v_mul_f32_e32 v125, v125, v147
	v_mul_f32_e32 v126, v126, v147
	v_mul_f32_e32 v127, v127, v147
	v_mul_f32_e32 v128, v128, v148
	v_mul_f32_e32 v129, v129, v148
	v_mul_f32_e32 v130, v130, v148
	v_mul_f32_e32 v131, v131, v148
	v_mul_f32_e32 v132, v132, v149
	v_mul_f32_e32 v133, v133, v149
	v_mul_f32_e32 v134, v134, v149
	v_mul_f32_e32 v135, v135, v149
	v_mul_f32_e32 v136, v136, v150
	v_mul_f32_e32 v137, v137, v150
	v_mul_f32_e32 v138, v138, v150
	v_mul_f32_e32 v139, v139, v150
	v_mul_f32_e32 v140, v140, v151
	v_mul_f32_e32 v141, v141, v151
	v_mul_f32_e32 v142, v142, v151
	v_mul_f32_e32 v143, v143, v151
.Lsl_in_nmul16:
	v_cvt_pk_bf16_f32 v86, v112, v116
	v_cvt_pk_bf16_f32 v87, v120, v124
	v_cvt_pk_bf16_f32 v88, v128, v132
	v_cvt_pk_bf16_f32 v89, v136, v140
	v_cvt_pk_bf16_f32 v90, v113, v117
	v_cvt_pk_bf16_f32 v91, v121, v125
	v_cvt_pk_bf16_f32 v92, v129, v133
	v_cvt_pk_bf16_f32 v93, v137, v141
	v_cvt_pk_bf16_f32 v94, v114, v118
	v_cvt_pk_bf16_f32 v95, v122, v126
	v_cvt_pk_bf16_f32 v96, v130, v134
	v_cvt_pk_bf16_f32 v97, v138, v142
	v_cvt_pk_bf16_f32 v98, v115, v119
	v_cvt_pk_bf16_f32 v99, v123, v127
	v_cvt_pk_bf16_f32 v100, v131, v135
	v_cvt_pk_bf16_f32 v101, v139, v143
	global_store_dwordx4 v111, v[86:89], s[24:25] sc1
	v_add_u32_e32 v111, s41, v111
	global_store_dwordx4 v111, v[90:93], s[24:25] sc1
	v_add_u32_e32 v111, s41, v111
	global_store_dwordx4 v111, v[94:97], s[24:25] sc1
	v_add_u32_e32 v111, s41, v111
	global_store_dwordx4 v111, v[98:101], s[24:25] sc1
	s_branch .Lsl_in_loop
.Lsl_in_pair:
	s_cmp_eq_u32 s43, 0
	s_cbranch_scc1 .Lsl_in_w817
	s_waitcnt vmcnt(10)
	s_branch .Lsl_in_wd18

; __device__ __forceinline__ void tr_item(const float* __restrict__ W, int K, int N, bf16_t* WT, const float* __restrict__ kscale, int rowmode, int item, int lane) {
;     const int nblk = N >> 5, kb = item / nblk, nb = item - kb * nblk;
;     const int c = lane >> 3, q = lane & 7, k0 = kb * 64 + c * 8, n0 = nb * 32 + q * 4;
;     f32x4 v[8];
; #pragma unroll
;     for (int i = 0; i < 8; ++i) v[i] = __builtin_nontemporal_load((const f32x4*)(W + (size_t)(k0 + i) * N + n0));
;     if (kscale) { const f32x4 s0 = *(const f32x4*)(kscale + k0), s1 = *(const f32x4*)(kscale + k0 + 4);
; #pragma unroll
;         for (int i = 0; i < 4; ++i) { v[i] = v[i] * s0[i]; v[4 + i] = v[4 + i] * s1[i]; } }
;     int drow;
;     if (rowmode == 0) drow = n0;
;     else if (rowmode == 3) { const int g = n0 - pg8::C_GA; drow = g < 0 ? n0 : pg8::C_GA + (((g & 2047) >> 7) << 8) + ((g >> 11) << 7) + (g & 127); }
;     else drow = ((n0 >> 7) << 8) + (n0 & 127) + (rowmode == 2 ? 128 : 0);
.Lsl_gu_rmd5:
	s_mul_i32 s19, s19, s41
	s_lshl_b32 s20, s17, 7
	s_add_i32 s19, s19, s20
	v_add_u32_e32 v45, s19, v105
	s_add_i32 s4, s4, 1024
	s_cmp_ge_u32 s4, s29
	s_cbranch_scc1 .Lsl_gu_pair
	s_add_i32 s16, s4, s44
	s_mul_i32 s17, s16, s38
	s_lshr_b32 s17, s17, s39
	s_mul_i32 s19, s17, s40
	s_sub_i32 s18, s16, s19
	s_mul_i32 s19, s17, s37
	s_lshl_b32 s20, s18, 7
	s_add_i32 s19, s19, s20
	v_add_u32_e32 v42, s19, v104
	s_cmp_eq_u32 s43, 0
	s_cbranch_scc1 .Lsl_gu_nks7
	s_lshl_b32 s19, s17, 8
	v_add_u32_e32 v43, s19, v110
	global_load_dwordx4 v[144:147], v43, s[26:27]
	global_load_dwordx4 v[148:151], v43, s[26:27] offset:16

; __device__ __forceinline__ unsigned cvt_pk_bf16(float lo, float hi) { unsigned r; asm volatile("v_cvt_pk_bf16_f32 %0, %1, %2" : "=v"(r) : "v"(lo), "v"(hi)); return r; }
; __device__ __forceinline__ void st16_wt(void* p, u32x4 v) { asm volatile("global_store_dwordx4 %0, %1, off sc1\n\ts_nop 1" :: "v"(p), "v"(v) : "memory"); }
; __device__ __forceinline__ void tr_item(const float* __restrict__ W, int K, int N, bf16_t* WT, const float* __restrict__ kscale, int rowmode, int item, int lane) {
;     ...
;     else drow = ((n0 >> 7) << 8) + (n0 & 127) + (rowmode == 2 ? 128 : 0);
; #pragma unroll
;     for (int e = 0; e < 4; ++e) { u32x4 o; o.x = cvt_pk_bf16(v[0][e], v[1][e]); o.y = cvt_pk_bf16(v[2][e], v[3][e]); o.z = cvt_pk_bf16(v[4][e], v[5][e]); o.w = cvt_pk_bf16(v[6][e], v[7][e]);
;         pg8::st16_wt(WT + (size_t)(drow + e) * K + k0, o); }
.Lsl_gu_rmd8:
	s_mul_i32 s19, s19, s41
	s_lshl_b32 s20, s17, 7
	s_add_i32 s19, s19, s20
	v_add_u32_e32 v111, s19, v105
	s_add_i32 s4, s4, 1024
	s_cmp_eq_u32 s43, 0
	s_cbranch_scc1 .Lsl_gu_w810
	s_waitcnt vmcnt(20)
	s_branch .Lsl_gu_wd11
